# EpiInproj256: permlane16_swap + 16 global_store_dwordx4 instead of 32 dwordx2 per wave and tile
# speedup vs baseline: 1.0177x; 1.0028x over previous
.LBB0_936:
	s_or_b64 exec, exec, s[8:9]
	v_ashrrev_i32_e32 v97, 31, v96
	v_lshl_add_u64 v[32:33], v[96:97], 1, v[32:33]
	v_lshl_add_u64 v[32:33], v[32:33], 0, v[128:129]
	v_mad_i64_i32 v[34:35], s[6:7], v64, v74, 0
	v_lshl_add_u64 v[34:35], v[34:35], 1, v[32:33]
	v_cvt_pk_bf16_f32 v226, v24, v25
	v_cvt_pk_bf16_f32 v227, v26, v27
	v_mad_i64_i32 v[24:25], s[6:7], v64, v73, 0
	v_cvt_pk_bf16_f32 v224, v28, v29
	v_cvt_pk_bf16_f32 v225, v30, v31
	v_lshl_add_u64 v[24:25], v[24:25], 1, v[32:33]
	v_cvt_pk_bf16_f32 v230, v16, v17
	v_cvt_pk_bf16_f32 v231, v18, v19
	s_nop 1
	v_permlane16_swap_b32 v224, v226
	v_permlane16_swap_b32 v225, v227
	v_lshl_add_u64 v[240:241], v[34:35], 0, v[244:245]
	global_store_dwordx4 v[240:241], v[224:227], off
	v_mad_i64_i32 v[16:17], s[6:7], v64, v72, 0
	v_cvt_pk_bf16_f32 v228, v20, v21
	v_cvt_pk_bf16_f32 v229, v22, v23
	v_lshl_add_u64 v[16:17], v[16:17], 1, v[32:33]
	v_cvt_pk_bf16_f32 v234, v8, v9
	v_cvt_pk_bf16_f32 v235, v10, v11
	s_nop 1
	v_permlane16_swap_b32 v228, v230
	v_permlane16_swap_b32 v229, v231
	v_lshl_add_u64 v[242:243], v[24:25], 0, v[244:245]
	global_store_dwordx4 v[242:243], v[228:231], off
	v_mad_i64_i32 v[8:9], s[6:7], v64, v67, 0
	v_cvt_pk_bf16_f32 v232, v12, v13
	v_cvt_pk_bf16_f32 v233, v14, v15
	v_lshl_add_u64 v[8:9], v[8:9], 1, v[32:33]
	v_cvt_pk_bf16_f32 v236, v4, v5
	v_cvt_pk_bf16_f32 v237, v6, v7
	v_cvt_pk_bf16_f32 v238, v0, v1
	v_cvt_pk_bf16_f32 v239, v2, v3
	s_andn2_b64 vcc, exec, s[12:13]
	s_mov_b32 s8, s16
	s_mov_b32 s18, s14
	s_nop 1
	v_permlane16_swap_b32 v232, v234
	v_permlane16_swap_b32 v233, v235
	v_lshl_add_u64 v[246:247], v[16:17], 0, v[244:245]
	global_store_dwordx4 v[246:247], v[232:235], off
	s_nop 1
	v_permlane16_swap_b32 v236, v238
	v_permlane16_swap_b32 v237, v239
	v_lshl_add_u64 v[248:249], v[8:9], 0, v[244:245]
	global_store_dwordx4 v[248:249], v[236:239], off
	s_cbranch_vccz .LBB0_968

.LBB0_945:
	v_bfe_u32 v244, v131, 4, 1
	v_mul_u32_u24_e32 v244, 24, v244
	v_mov_b32_e32 v245, 0
	v_add_u32_e32 v153, s8, v150
	s_movk_i32 s6, 0x1ff
	v_cmp_lt_i32_e32 vcc, s6, v153
	v_mov_b64_e32 v[142:143], 0x800
	v_mov_b64_e32 v[146:147], s[82:83]
	v_mov_b64_e32 v[144:145], 0x800
	v_mov_b32_e32 v148, v153
	s_and_saveexec_b64 s[8:9], vcc
	s_cbranch_execz .LBB0_951
	s_movk_i32 s6, 0x4ff
	v_cmp_lt_u32_e64 s[6:7], s6, v153
	v_mov_b64_e32 v[146:147], s[50:51]
	s_and_saveexec_b64 s[30:31], s[6:7]
	s_xor_b64 s[6:7], exec, s[30:31]
	v_add_u32_e32 v148, 0xfffffd00, v153
	v_mov_b64_e32 v[146:147], s[82:83]
	s_or_saveexec_b64 s[6:7], s[6:7]
	v_mov_b64_e32 v[144:145], 0x800
	s_xor_b64 exec, exec, s[6:7]
	v_add_u32_e32 v148, 0xfffffe00, v153
	v_mov_b64_e32 v[144:145], 0x300
	s_or_b64 exec, exec, s[6:7]
.LBB0_951:
	s_or_b64 exec, exec, s[8:9]
	v_ashrrev_i32_e32 v149, 31, v148
	v_add_u32_e32 v145, s18, v133
	v_lshl_add_u64 v[146:147], v[148:149], 1, v[146:147]
	v_lshl_add_u64 v[146:147], v[146:147], 0, v[128:129]
	v_mad_i64_i32 v[148:149], s[6:7], v144, v145, 0
	v_add_u32_e32 v156, 16, v145
	v_lshl_add_u64 v[148:149], v[148:149], 1, v[146:147]
	v_cvt_pk_bf16_f32 v210, v120, v121
	v_cvt_pk_bf16_f32 v211, v122, v123
	v_mad_i64_i32 v[120:121], s[6:7], v144, v156, 0
	v_add_u32_e32 v155, 32, v145
	v_cvt_pk_bf16_f32 v208, v124, v125
	v_cvt_pk_bf16_f32 v209, v126, v127
	v_lshl_add_u64 v[120:121], v[120:121], 1, v[146:147]
	v_cvt_pk_bf16_f32 v214, v112, v113
	v_cvt_pk_bf16_f32 v215, v114, v115
	s_nop 1
	v_permlane16_swap_b32 v208, v210
	v_permlane16_swap_b32 v209, v211
	v_lshl_add_u64 v[240:241], v[148:149], 0, v[244:245]
	global_store_dwordx4 v[240:241], v[208:211], off
	v_mad_i64_i32 v[112:113], s[6:7], v144, v155, 0
	v_add_u32_e32 v154, 48, v145
	v_cvt_pk_bf16_f32 v212, v116, v117
	v_cvt_pk_bf16_f32 v213, v118, v119
	v_lshl_add_u64 v[112:113], v[112:113], 1, v[146:147]
	v_cvt_pk_bf16_f32 v218, v104, v105
	v_cvt_pk_bf16_f32 v219, v106, v107
	s_nop 1
	v_permlane16_swap_b32 v212, v214
	v_permlane16_swap_b32 v213, v215
	v_lshl_add_u64 v[242:243], v[120:121], 0, v[244:245]
	global_store_dwordx4 v[242:243], v[212:215], off
	v_mad_i64_i32 v[104:105], s[6:7], v144, v154, 0
	v_cvt_pk_bf16_f32 v216, v108, v109
	v_cvt_pk_bf16_f32 v217, v110, v111
	v_lshl_add_u64 v[104:105], v[104:105], 1, v[146:147]
	v_cvt_pk_bf16_f32 v222, v96, v97
	v_cvt_pk_bf16_f32 v223, v98, v99
	s_nop 1
	v_permlane16_swap_b32 v216, v218
	v_permlane16_swap_b32 v217, v219
	v_lshl_add_u64 v[246:247], v[112:113], 0, v[244:245]
	global_store_dwordx4 v[246:247], v[216:219], off
	v_cvt_pk_bf16_f32 v220, v100, v101
	v_cvt_pk_bf16_f32 v221, v102, v103
	v_add_u32_e32 v96, 0x80, v153
	s_movk_i32 s6, 0x17f
	s_nop 1
	v_permlane16_swap_b32 v220, v222
	v_permlane16_swap_b32 v221, v223
	v_lshl_add_u64 v[248:249], v[104:105], 0, v[244:245]
	global_store_dwordx4 v[248:249], v[220:223], off
	v_cmp_lt_i32_e64 s[6:7], s6, v153
	v_mov_b64_e32 v[98:99], s[82:83]
	v_mov_b32_e32 v100, v96
	s_and_saveexec_b64 s[18:19], s[6:7]
	s_cbranch_execz .LBB0_957
	s_movk_i32 s8, 0x4ff
	v_cmp_lt_u32_e64 s[8:9], s8, v96
	v_mov_b64_e32 v[98:99], s[50:51]
	s_and_saveexec_b64 s[30:31], s[8:9]
	s_xor_b64 s[8:9], exec, s[30:31]
	v_add_u32_e32 v100, 0xfffffd80, v153
	v_mov_b64_e32 v[98:99], s[82:83]
	s_or_saveexec_b64 s[8:9], s[8:9]
	v_mov_b64_e32 v[142:143], 0x800
	s_xor_b64 exec, exec, s[8:9]
	v_add_u32_e32 v100, 0xfffffe80, v153
	v_mov_b64_e32 v[142:143], 0x300
	s_or_b64 exec, exec, s[8:9]
.LBB0_957:
	s_or_b64 exec, exec, s[18:19]
	v_ashrrev_i32_e32 v101, 31, v100
	v_lshl_add_u64 v[98:99], v[100:101], 1, v[98:99]
	v_lshl_add_u64 v[98:99], v[98:99], 0, v[128:129]
	v_mad_i64_i32 v[100:101], s[8:9], v142, v145, 0
	v_lshl_add_u64 v[100:101], v[100:101], 1, v[98:99]
	v_cvt_pk_bf16_f32 v226, v88, v89
	v_cvt_pk_bf16_f32 v227, v90, v91
	v_mad_i64_i32 v[88:89], s[8:9], v142, v156, 0
	v_cvt_pk_bf16_f32 v224, v92, v93
	v_cvt_pk_bf16_f32 v225, v94, v95
	v_lshl_add_u64 v[88:89], v[88:89], 1, v[98:99]
	v_cvt_pk_bf16_f32 v230, v80, v81
	v_cvt_pk_bf16_f32 v231, v82, v83
	s_nop 1
	v_permlane16_swap_b32 v224, v226
	v_permlane16_swap_b32 v225, v227
	v_lshl_add_u64 v[240:241], v[100:101], 0, v[244:245]
	global_store_dwordx4 v[240:241], v[224:227], off
	v_mad_i64_i32 v[80:81], s[8:9], v142, v155, 0
	v_cvt_pk_bf16_f32 v228, v84, v85
	v_cvt_pk_bf16_f32 v229, v86, v87
	v_lshl_add_u64 v[80:81], v[80:81], 1, v[98:99]
	v_cvt_pk_bf16_f32 v234, v72, v73
	v_cvt_pk_bf16_f32 v235, v74, v75
	s_nop 1
	v_permlane16_swap_b32 v228, v230
	v_permlane16_swap_b32 v229, v231
	v_lshl_add_u64 v[242:243], v[88:89], 0, v[244:245]
	global_store_dwordx4 v[242:243], v[228:231], off
	v_mad_i64_i32 v[72:73], s[8:9], v142, v154, 0
	v_cvt_pk_bf16_f32 v232, v76, v77
	v_cvt_pk_bf16_f32 v233, v78, v79
	v_lshl_add_u64 v[72:73], v[72:73], 1, v[98:99]
	v_cvt_pk_bf16_f32 v236, v68, v69
	v_cvt_pk_bf16_f32 v237, v70, v71
	v_cvt_pk_bf16_f32 v238, v64, v65
	v_cvt_pk_bf16_f32 v239, v66, v67
	s_nop 1
	v_permlane16_swap_b32 v232, v234
	v_permlane16_swap_b32 v233, v235
	v_lshl_add_u64 v[246:247], v[80:81], 0, v[244:245]
	global_store_dwordx4 v[246:247], v[232:235], off
	s_nop 1
	v_permlane16_swap_b32 v236, v238
	v_permlane16_swap_b32 v237, v239
	v_lshl_add_u64 v[248:249], v[72:73], 0, v[244:245]
	global_store_dwordx4 v[248:249], v[236:239], off
	v_mov_b64_e32 v[64:65], 0x800
	v_mov_b64_e32 v[68:69], s[82:83]
	v_mov_b64_e32 v[66:67], 0x800
	v_mov_b32_e32 v70, v153
	s_and_saveexec_b64 s[8:9], vcc
	s_cbranch_execz .LBB0_963
	s_movk_i32 s15, 0x4ff
	v_cmp_lt_u32_e32 vcc, s15, v153
	v_mov_b64_e32 v[68:69], s[50:51]
	s_and_saveexec_b64 s[18:19], vcc
	s_xor_b64 s[18:19], exec, s[18:19]
	v_add_u32_e32 v70, 0xfffffd00, v153
	v_mov_b64_e32 v[68:69], s[82:83]
	s_or_saveexec_b64 s[18:19], s[18:19]
	v_mov_b64_e32 v[66:67], 0x800
	s_xor_b64 exec, exec, s[18:19]
	v_add_u32_e32 v70, 0xfffffe00, v153
	v_mov_b64_e32 v[66:67], 0x300
	s_or_b64 exec, exec, s[18:19]
.LBB0_963:
	s_or_b64 exec, exec, s[8:9]
	v_ashrrev_i32_e32 v71, 31, v70
	v_add_u32_e32 v74, 0x80, v145
	v_lshl_add_u64 v[68:69], v[70:71], 1, v[68:69]
	v_lshl_add_u64 v[68:69], v[68:69], 0, v[128:129]
	v_mad_i64_i32 v[70:71], s[8:9], v66, v74, 0
	v_add_u32_e32 v73, 0x90, v145
	v_lshl_add_u64 v[70:71], v[70:71], 1, v[68:69]
	v_cvt_pk_bf16_f32 v210, v56, v57
	v_cvt_pk_bf16_f32 v211, v58, v59
	v_mad_i64_i32 v[56:57], s[8:9], v66, v73, 0
	v_add_u32_e32 v72, 0xa0, v145
	v_cvt_pk_bf16_f32 v208, v60, v61
	v_cvt_pk_bf16_f32 v209, v62, v63
	v_lshl_add_u64 v[56:57], v[56:57], 1, v[68:69]
	v_cvt_pk_bf16_f32 v214, v48, v49
	v_cvt_pk_bf16_f32 v215, v50, v51
	s_nop 1
	v_permlane16_swap_b32 v208, v210
	v_permlane16_swap_b32 v209, v211
	v_lshl_add_u64 v[240:241], v[70:71], 0, v[244:245]
	global_store_dwordx4 v[240:241], v[208:211], off
	v_mad_i64_i32 v[48:49], s[8:9], v66, v72, 0
	v_add_u32_e32 v67, 0xb0, v145
	v_cvt_pk_bf16_f32 v212, v52, v53
	v_cvt_pk_bf16_f32 v213, v54, v55
	v_lshl_add_u64 v[48:49], v[48:49], 1, v[68:69]
	v_cvt_pk_bf16_f32 v218, v40, v41
	v_cvt_pk_bf16_f32 v219, v42, v43
	s_nop 1
	v_permlane16_swap_b32 v212, v214
	v_permlane16_swap_b32 v213, v215
	v_lshl_add_u64 v[242:243], v[56:57], 0, v[244:245]
	global_store_dwordx4 v[242:243], v[212:215], off
	v_mad_i64_i32 v[40:41], s[8:9], v66, v67, 0
	v_cvt_pk_bf16_f32 v216, v44, v45
	v_cvt_pk_bf16_f32 v217, v46, v47
	v_lshl_add_u64 v[40:41], v[40:41], 1, v[68:69]
	v_cvt_pk_bf16_f32 v222, v32, v33
	v_cvt_pk_bf16_f32 v223, v34, v35
	s_nop 1
	v_permlane16_swap_b32 v216, v218
	v_permlane16_swap_b32 v217, v219
	v_lshl_add_u64 v[246:247], v[48:49], 0, v[244:245]
	global_store_dwordx4 v[246:247], v[216:219], off
	v_cvt_pk_bf16_f32 v220, v36, v37
	v_cvt_pk_bf16_f32 v221, v38, v39
	v_mov_b64_e32 v[32:33], s[82:83]
	s_nop 1
	v_permlane16_swap_b32 v220, v222
	v_permlane16_swap_b32 v221, v223
	v_lshl_add_u64 v[248:249], v[40:41], 0, v[244:245]
	global_store_dwordx4 v[248:249], v[220:223], off
	s_and_saveexec_b64 s[8:9], s[6:7]
	s_cbranch_execz .LBB0_936
	s_movk_i32 s6, 0x4ff
	v_cmp_lt_u32_e32 vcc, s6, v96
	v_mov_b64_e32 v[32:33], s[50:51]
	s_and_saveexec_b64 s[6:7], vcc
	s_xor_b64 s[6:7], exec, s[6:7]
	v_add_u32_e32 v96, 0xfffffd80, v153
	v_mov_b64_e32 v[32:33], s[82:83]
	s_or_saveexec_b64 s[6:7], s[6:7]
	v_mov_b64_e32 v[64:65], 0x800
	s_xor_b64 exec, exec, s[6:7]
	s_cbranch_execz .LBB0_935
	v_add_u32_e32 v96, 0xfffffe80, v153
	v_mov_b64_e32 v[64:65], 0x300
	s_branch .LBB0_935
